# phase-0 transpose loop: load-wait ladder leaves the previous tile's stores in flight (on v9)
# baseline (speedup 1.0000x reference)
; DI void phase0(const Params& p, char* smem, int wv) {
;     ...
;     const int row0 = tid >> 5, c4 = (tid & 31) * 4;
;     const int g = gridDim.x;
;     int ti = (blockIdx.x + g - (N_MOD % g)) % g;
;     f32x4 v[8];
;     const float* src; u16* dst; int N, kt, nt;
;     if (ti < N_TR) {
;       tr_desc(ti, src, dst, N, kt, nt);
; #pragma unroll
;       for (int i = 0; i < 8; ++i) v[i] = *(const f32x4*)(src + (size_t)(kt * 128 + row0 + 16 * i) * N + nt * 128 + c4);
;     }
.LBB0_586:
	s_lshl_b32 s6, s12, 7
	s_ashr_i32 s7, s6, 31
	s_lshl_b64 s[6:7], s[6:7], 2
	v_ashrrev_i32_e32 v36, 5, v34
	s_waitcnt vmcnt(11)
	v_and_b32_e32 v40, 0x7c, v2
	s_add_u32 s4, s4, s6
	s_addc_u32 s5, s5, s7
	v_lshlrev_b32_e32 v0, 2, v40
	s_waitcnt vmcnt(4)
	v_lshl_add_u32 v30, s13, 7, v36
	v_lshl_add_u64 v[26:27], s[4:5], 0, v[0:1]
	v_mad_i64_i32 v[2:3], s[4:5], s2, v30, 0
	v_add_u32_e32 v4, 16, v30
	v_add_u32_e32 v10, 32, v30
	v_add_u32_e32 v12, 48, v30
	v_add_u32_e32 v18, 64, v30
	v_add_u32_e32 v20, 0x50, v30
	v_add_u32_e32 v28, 0x60, v30
	v_add_u32_e32 v30, 0x70, v30
	v_mad_i64_i32 v[4:5], s[4:5], s2, v4, 0
	v_mad_i64_i32 v[10:11], s[4:5], s2, v10, 0
	v_mad_i64_i32 v[12:13], s[4:5], s2, v12, 0
	v_mad_i64_i32 v[18:19], s[4:5], s2, v18, 0
	v_mad_i64_i32 v[20:21], s[4:5], s2, v20, 0
	v_mad_i64_i32 v[28:29], s[4:5], s2, v28, 0
	v_mad_i64_i32 v[30:31], s[2:3], s2, v30, 0
	v_lshl_add_u64 v[2:3], v[2:3], 2, v[26:27]
	v_lshl_add_u64 v[6:7], v[4:5], 2, v[26:27]
	v_lshl_add_u64 v[10:11], v[10:11], 2, v[26:27]
	v_lshl_add_u64 v[14:15], v[12:13], 2, v[26:27]
	v_lshl_add_u64 v[18:19], v[18:19], 2, v[26:27]
	v_lshl_add_u64 v[22:23], v[20:21], 2, v[26:27]
	v_lshl_add_u64 v[28:29], v[28:29], 2, v[26:27]
	v_lshl_add_u64 v[30:31], v[30:31], 2, v[26:27]
	global_load_dwordx4 v[2:5], v[2:3], off
	s_nop 0
	global_load_dwordx4 v[6:9], v[6:7], off
	s_nop 0
	global_load_dwordx4 v[10:13], v[10:11], off
	s_nop 0
	global_load_dwordx4 v[14:17], v[14:15], off
	s_nop 0
	global_load_dwordx4 v[18:21], v[18:19], off
	s_nop 0
	global_load_dwordx4 v[22:25], v[22:23], off
	s_nop 0
	global_load_dwordx4 v[26:29], v[28:29], off
	s_nop 0
	global_load_dwordx4 v[30:33], v[30:31], off
	v_ashrrev_i32_e32 v37, 4, v34
	v_lshlrev_b32_e32 v34, 3, v38
	v_and_b32_e32 v34, 0x78, v34
	v_lshlrev_b32_e32 v35, 2, v37
	s_movk_i32 s2, 0x204
	v_mad_u32_u24 v38, v34, s2, v35
	v_mul_lo_u32 v35, v36, s2
	v_add_u32_e32 v39, v0, v35
	v_lshlrev_b32_e32 v0, 2, v40
	v_lshlrev_b32_e32 v34, 1, v34
	s_mov_b32 s15, s12
	s_mov_b32 s14, s13
	s_mov_b64 s[2:3], s[0:1]
	s_waitcnt vmcnt(0)
	s_branch .LBB0_589

; DI void phase0(const Params& p, char* smem, int wv) {
;     ...
;     auto tr_desc = [&](int ti, const float*& src, u16*& dst, int& N, int& kt, int& nt) {
;       if (ti < N_TRIN) {
;         const int l = ti / 896, rem = ti % 896; kt = rem / 56; nt = rem % 56; N = INW;
;         src = p.w_in + (size_t)l * DM * INW; dst = p.wt_in + (size_t)l * INW * DM;
;       } else {
;         const int t2 = ti - N_TRIN;
;         const int l = t2 / 256, rem = t2 % 256; kt = rem / 16; nt = rem % 16; N = DM;
;         src = p.w_out + (size_t)l * DM * DM; dst = p.wt_out + (size_t)l * DM * DM;
;       }
;     ...
;     for (; ti < N_TR; ti += g) {
; #pragma unroll
;       for (int i = 0; i < 8; ++i) {
;         float* d = sf + (row0 + 16 * i) * 129 + c4;
;         d[0] = v[i][0]; d[1] = v[i][1]; d[2] = v[i][2]; d[3] = v[i][3];
;       }
;       __syncthreads();
;       u16* dcur = dst; const int ktc = kt, ntc = nt;
;       if (ti + g < N_TR) {
;         tr_desc(ti + g, src, dst, N, kt, nt);
.LBB0_589:
	v_add_u32_e32 v35, 0x2040, v39
	s_waitcnt vmcnt(11)
	ds_write2_b32 v39, v2, v3 offset1:1
	ds_write2_b32 v39, v4, v5 offset0:2 offset1:3
	s_waitcnt vmcnt(10)
	ds_write2_b32 v35, v6, v7 offset1:1
	v_add_u32_e32 v35, 0x2048, v39
	ds_write2_b32 v35, v8, v9 offset1:1
	v_add_u32_e32 v35, 0x4080, v39
	s_waitcnt vmcnt(9)
	ds_write2_b32 v35, v10, v11 offset1:1
	v_add_u32_e32 v35, 0x4088, v39
	ds_write2_b32 v35, v12, v13 offset1:1
	v_add_u32_e32 v35, 0x60c0, v39
	s_waitcnt vmcnt(8)
	ds_write2_b32 v35, v14, v15 offset1:1
	v_add_u32_e32 v35, 0x60c8, v39
	ds_write2_b32 v35, v16, v17 offset1:1
	v_add_u32_e32 v35, 0x8100, v39
	s_waitcnt vmcnt(7)
	ds_write2_b32 v35, v18, v19 offset1:1
	v_add_u32_e32 v35, 0x8108, v39
	ds_write2_b32 v35, v20, v21 offset1:1
	v_add_u32_e32 v35, 0xa140, v39
	s_waitcnt vmcnt(6)
	ds_write2_b32 v35, v22, v23 offset1:1
	v_add_u32_e32 v35, 0xa148, v39
	ds_write2_b32 v35, v24, v25 offset1:1
	v_add_u32_e32 v35, 0xc180, v39
	s_add_i32 s11, s11, s10
	s_waitcnt vmcnt(5)
	ds_write2_b32 v35, v26, v27 offset1:1
	v_add_u32_e32 v35, 0xc188, v39
	s_cmpk_gt_i32 s11, 0x11ff
	ds_write2_b32 v35, v28, v29 offset1:1
	v_add_u32_e32 v35, 0xe1c0, v39
	s_cselect_b64 s[4:5], -1, 0
	s_waitcnt vmcnt(4)
	ds_write2_b32 v35, v30, v31 offset1:1
	v_add_u32_e32 v35, 0xe1c8, v39
	s_and_b64 vcc, exec, s[4:5]
	ds_write2_b32 v35, v32, v33 offset1:1
	s_waitcnt lgkmcnt(0)
	s_barrier
	s_cbranch_vccnz .LBB0_588
	s_cmpk_gt_i32 s11, 0xdff
	s_mov_b64 s[6:7], -1
	s_cbranch_scc0 .LBB0_592
	s_add_i32 s2, s11, 0xfffff200
	s_mov_b64 s[78:79], s[54:55]
	s_lshr_b32 s18, s2, 8
	s_mov_b64 s[76:77], s[52:53]
	s_mov_b64 s[74:75], s[50:51]
	s_mov_b64 s[72:73], s[48:49]
	s_mov_b64 s[70:71], s[46:47]
	s_mov_b64 s[68:69], s[44:45]
	s_mov_b64 s[66:67], s[42:43]
	s_mov_b64 s[64:65], s[40:41]
	v_readlane_b32 s36, v253, 21
	s_bfe_u32 s14, s11, 0x40004
	s_and_b32 s15, s11, 15
	s_lshl_b64 s[2:3], s[18:19], 24
	v_readlane_b32 s38, v253, 23
	v_readlane_b32 s39, v253, 24
	s_add_u32 s8, s38, s2
	v_readlane_b32 s46, v253, 31
	s_addc_u32 s9, s39, s3
	s_lshl_b64 s[2:3], s[18:19], 23
	v_readlane_b32 s40, v253, 25
	v_readlane_b32 s41, v253, 26
	v_readlane_b32 s42, v253, 27
	v_readlane_b32 s43, v253, 28
	v_readlane_b32 s44, v253, 29
	v_readlane_b32 s45, v253, 30
	v_readlane_b32 s47, v253, 32
	v_readlane_b32 s48, v253, 33
	v_readlane_b32 s49, v253, 34
	v_readlane_b32 s50, v253, 35
	v_readlane_b32 s51, v253, 36
	s_add_u32 s2, s46, s2
	s_addc_u32 s3, s47, s3
	s_mov_b64 s[40:41], s[64:65]
	v_readlane_b32 s37, v253, 22
	s_mov_b32 s18, 0x1e000
	s_mov_b64 s[42:43], s[66:67]
	s_mov_b64 s[44:45], s[68:69]
	s_mov_b64 s[46:47], s[70:71]
	s_mov_b64 s[48:49], s[72:73]
	s_mov_b64 s[50:51], s[74:75]
	s_mov_b64 s[52:53], s[76:77]
	s_mov_b64 s[54:55], s[78:79]
	s_mov_b64 s[6:7], 0
